# P5 K-loop split per half-workgroup: leading half waits after its MFMA block, trailing half issues next segment's LDS-DMA loads inside its MFMA block (wider load window)
# baseline (speedup 1.0000x reference)
; #define PG8_STAGE(bufoff, gbase, voff) do { _Pragma("unroll") for (int _i = 0; _i < 2; ++_i) \
;         __builtin_amdgcn_global_load_lds((const unsigned*)((const char*)(gbase) + (voff)[_i]), (PG8_LAS unsigned*)(lds + (bufoff) + ldsw + _i * 8192), 16, 0, 0); } while (0)
; #define PG8_LDA(dst, b, h) do { _Pragma("unroll") for (int m = 0; m < 4; ++m) _Pragma("unroll") for (int k = 0; k < 2; ++k) dst[m][k] = *(const PG8_LAS bf16x8*)(lds + PG8_SA(b, h) + aoff + m * 2048 + k * 1024); } while (0)
; #define PG8_LDB(dst, b, h) do { _Pragma("unroll") for (int n = 0; n < 2; ++n) _Pragma("unroll") for (int k = 0; k < 2; ++k) dst[n][k] = *(const PG8_LAS bf16x8*)(lds + PG8_SB(b, h) + boff + n * 2048 + k * 1024); } while (0)
; #define PG8_MMA(ai, bj, At, Bt) do { __builtin_amdgcn_s_setprio(1); _Pragma("unroll") for (int m = 0; m < 4; ++m) _Pragma("unroll") for (int n = 0; n < 2; ++n) _Pragma("unroll") for (int k = 0; k < 2; ++k) \
;         acc[ai][bj][m][n] = __builtin_amdgcn_mfma_f32_16x16x32_bf16(Bt[n][k], At[m][k], acc[ai][bj][m][n], 0, 0, 0); __builtin_amdgcn_s_setprio(0); } while (0)
; #define PG8_WAIT_V(n) asm volatile("s_waitcnt vmcnt(" #n ")" ::: "memory")
; #define PG8_WAIT_L(n) asm volatile("s_waitcnt lgkmcnt(" #n ")" ::: "memory")
; #define PG8_BAR __builtin_amdgcn_s_barrier()
; template <class Epi, class Sched, bool ALIGN_EPI = false, bool SP2 = false>
; __device__ __forceinline__ void gemm_phase(PG8_LAS unsigned char* lds, const Gemm g, const Sched& S, const Epi& E) {
;     ...
;         const bool has_next = S.next(ui + 1, nxt);
;         const char* nA = has_next ? (const char*)g.A + (size_t)nxt.pm * tstep : cA; const char* nB = has_next ? (const char*)g.Bt + (size_t)nxt.pn * tstep : cB;
;         for (int t = 0; t < nt; t += 2) {
;             const bool last = (t == nt - 2);
;             const char* a1 = cA + (size_t)(t + 1) * kstep;
;             const char* a2 = last ? nA : cA + (size_t)(t + 2) * kstep; const char* b2 = last ? nB : cB + (size_t)(t + 2) * kstep;
;             const char* a3 = a2 + kstep; const char* b3 = b2 + kstep;
;             if (last && has_next) S.a_ready(nxt);
;             if constexpr (SP2) {
;             PG8_LDB(B0, 0, 0); PG8_LDB(B1, 0, 1); PG8_SCHED; PG8_LDA(At, 0, 0); PG8_STAGE(PG8_SA(1, 1), a1 + hstep, voffA);
;             PG8_WAIT_V(8); PG8_WAIT_L(0); PG8_BAR; PG8_MMA(0, 0, At, B0); PG8_MMA(0, 1, At, B1); PG8_BAR; PG8_SCHED;
.LBB0_1423:
	s_add_u32 s12, s12, 0xb4000
	s_addc_u32 s13, s13, 0
	s_add_u32 s36, s36, 0x8000
	s_addc_u32 s37, s37, 0
	s_mov_b32 s57, -2
	ds_read_b128 v[136:139], v143
	ds_read_b128 v[146:149], v143 offset:1024
	ds_read_b128 v[150:153], v143 offset:2048
	ds_read_b128 v[154:157], v143 offset:3072
	ds_read_b128 v[158:161], v144
	ds_read_b128 v[162:165], v144 offset:1024
	ds_read_b128 v[166:169], v144 offset:2048
	ds_read_b128 v[170:173], v144 offset:3072
	s_add_u32 s58, s12, 0xfff54000
	s_addc_u32 s59, s13, -1
	s_cmp_eq_u32 s57, 40
	s_cselect_b32 s59, s3, s59
	s_cselect_b32 s58, s2, s58
	s_cselect_b32 s61, s35, s37
	s_cselect_b32 s60, s34, s36
	v_lshl_add_u64 v[198:199], s[12:13], 0, v[128:129]
	s_add_i32 m0, s39, 0xc000
	ds_read_b128 v[174:177], v145
	ds_read_b128 v[178:181], v145 offset:1024
	ds_read_b128 v[182:185], v145 offset:2048
	ds_read_b128 v[186:189], v145 offset:3072
	ds_read_b128 v[190:193], v145 offset:4096
	ds_read_b128 v[194:197], v145 offset:5120
	ds_read_b128 v[202:205], v145 offset:6144
	ds_read_b128 v[206:209], v145 offset:7168
	global_load_lds_dwordx4 v[198:199], off
	v_lshl_add_u64 v[198:199], v[198:199], 0, s[10:11]
	s_add_i32 m0, s39, 0xe000
	s_nop 0
	global_load_lds_dwordx4 v[198:199], off
	s_waitcnt vmcnt(8)
	s_waitcnt lgkmcnt(0)
	s_barrier
	s_setprio 1
	s_waitcnt lgkmcnt(0)
	v_mfma_f32_16x16x32_bf16 v[124:127], v[136:139], v[174:177], 0
	v_mfma_f32_16x16x32_bf16 v[120:123], v[150:153], v[174:177], 0
	v_mfma_f32_16x16x32_bf16 v[108:111], v[136:139], v[182:185], 0
	v_mfma_f32_16x16x32_bf16 v[104:107], v[150:153], v[182:185], 0
	v_mfma_f32_16x16x32_bf16 v[92:95], v[136:139], v[190:193], 0
	v_mfma_f32_16x16x32_bf16 v[88:91], v[150:153], v[190:193], 0
	v_mfma_f32_16x16x32_bf16 v[76:79], v[136:139], v[202:205], 0
	v_mfma_f32_16x16x32_bf16 v[72:75], v[150:153], v[202:205], 0
	v_mfma_f32_16x16x32_bf16 v[124:127], v[146:149], v[178:181], v[124:127]
	v_mfma_f32_16x16x32_bf16 v[120:123], v[154:157], v[178:181], v[120:123]
	v_mfma_f32_16x16x32_bf16 v[108:111], v[146:149], v[186:189], v[108:111]
	v_mfma_f32_16x16x32_bf16 v[104:107], v[154:157], v[186:189], v[104:107]
	v_mfma_f32_16x16x32_bf16 v[92:95], v[146:149], v[194:197], v[92:95]
	v_mfma_f32_16x16x32_bf16 v[88:91], v[154:157], v[194:197], v[88:91]
	v_mfma_f32_16x16x32_bf16 v[76:79], v[146:149], v[206:209], v[76:79]
	v_mfma_f32_16x16x32_bf16 v[72:75], v[154:157], v[206:209], v[72:75]
	s_setprio 0
	s_setprio 1
	v_mfma_f32_16x16x32_bf16 v[116:119], v[158:161], v[174:177], 0
	v_mfma_f32_16x16x32_bf16 v[112:115], v[166:169], v[174:177], 0
	v_mfma_f32_16x16x32_bf16 v[100:103], v[158:161], v[182:185], 0
	v_mfma_f32_16x16x32_bf16 v[96:99], v[166:169], v[182:185], 0
	v_mfma_f32_16x16x32_bf16 v[84:87], v[158:161], v[190:193], 0
	v_mfma_f32_16x16x32_bf16 v[80:83], v[166:169], v[190:193], 0
	v_mfma_f32_16x16x32_bf16 v[68:71], v[158:161], v[202:205], 0
	v_mfma_f32_16x16x32_bf16 v[64:67], v[166:169], v[202:205], 0
	v_mfma_f32_16x16x32_bf16 v[116:119], v[162:165], v[178:181], v[116:119]
	v_mfma_f32_16x16x32_bf16 v[112:115], v[170:173], v[178:181], v[112:115]
	v_mfma_f32_16x16x32_bf16 v[100:103], v[162:165], v[186:189], v[100:103]
	v_mfma_f32_16x16x32_bf16 v[96:99], v[170:173], v[186:189], v[96:99]
	v_mfma_f32_16x16x32_bf16 v[84:87], v[162:165], v[194:197], v[84:87]
	v_mfma_f32_16x16x32_bf16 v[80:83], v[170:173], v[194:197], v[80:83]
	v_mfma_f32_16x16x32_bf16 v[68:71], v[162:165], v[206:209], v[68:71]
	v_mfma_f32_16x16x32_bf16 v[64:67], v[170:173], v[206:209], v[64:67]
	s_setprio 0
	s_barrier
	v_lshl_add_u64 v[198:199], s[60:61], 0, v[128:129]
	s_add_i32 s60, s51, s38
	s_mov_b32 m0, s60
	ds_read_b128 v[174:177], v145 offset:16384
	ds_read_b128 v[178:181], v145 offset:17408
	ds_read_b128 v[182:185], v145 offset:18432
	ds_read_b128 v[186:189], v145 offset:19456
	ds_read_b128 v[190:193], v145 offset:20480
	ds_read_b128 v[194:197], v145 offset:21504
	ds_read_b128 v[202:205], v145 offset:22528
	ds_read_b128 v[206:209], v145 offset:23552
	global_load_lds_dwordx4 v[198:199], off
	v_lshl_add_u64 v[210:211], v[198:199], 0, s[10:11]
	s_add_i32 m0, s60, 0x2000
	s_add_i32 s60, s52, s38
	global_load_lds_dwordx4 v[210:211], off
	v_lshl_add_u64 v[210:211], v[198:199], 0, s[14:15]
	s_mov_b32 m0, s60
	s_nop 0
	global_load_lds_dwordx4 v[210:211], off
	v_lshl_add_u64 v[210:211], v[198:199], 0, s[16:17]
	s_add_i32 m0, s60, 0x2000
	s_nop 0
	global_load_lds_dwordx4 v[210:211], off
	v_lshl_add_u64 v[210:211], s[58:59], 0, v[128:129]
	s_mov_b32 m0, s39
	v_lshl_add_u64 v[212:213], v[210:211], 0, s[10:11]
	global_load_lds_dwordx4 v[210:211], off
	s_mov_b32 m0, s40
	s_nop 0
	global_load_lds_dwordx4 v[212:213], off
	s_waitcnt vmcnt(8)
	s_waitcnt lgkmcnt(0)
	s_barrier
; #define PG8_STAGE(bufoff, gbase, voff) do { _Pragma("unroll") for (int _i = 0; _i < 2; ++_i) \
;         __builtin_amdgcn_global_load_lds((const unsigned*)((const char*)(gbase) + (voff)[_i]), (PG8_LAS unsigned*)(lds + (bufoff) + ldsw + _i * 8192), 16, 0, 0); } while (0)
; #define PG8_LDA(dst, b, h) do { _Pragma("unroll") for (int m = 0; m < 4; ++m) _Pragma("unroll") for (int k = 0; k < 2; ++k) dst[m][k] = *(const PG8_LAS bf16x8*)(lds + PG8_SA(b, h) + aoff + m * 2048 + k * 1024); } while (0)
; #define PG8_LDB(dst, b, h) do { _Pragma("unroll") for (int n = 0; n < 2; ++n) _Pragma("unroll") for (int k = 0; k < 2; ++k) dst[n][k] = *(const PG8_LAS bf16x8*)(lds + PG8_SB(b, h) + boff + n * 2048 + k * 1024); } while (0)
; #define PG8_MMA(ai, bj, At, Bt) do { __builtin_amdgcn_s_setprio(1); _Pragma("unroll") for (int m = 0; m < 4; ++m) _Pragma("unroll") for (int n = 0; n < 2; ++n) _Pragma("unroll") for (int k = 0; k < 2; ++k) \
;         acc[ai][bj][m][n] = __builtin_amdgcn_mfma_f32_16x16x32_bf16(Bt[n][k], At[m][k], acc[ai][bj][m][n], 0, 0, 0); __builtin_amdgcn_s_setprio(0); } while (0)
; #define PG8_WAIT_V(n) asm volatile("s_waitcnt vmcnt(" #n ")" ::: "memory")
; #define PG8_WAIT_L(n) asm volatile("s_waitcnt lgkmcnt(" #n ")" ::: "memory")
; #define PG8_BAR __builtin_amdgcn_s_barrier()
; #define PG8_SCHED __builtin_amdgcn_sched_barrier(0)
; template <class Epi, class Sched, bool ALIGN_EPI = false, bool SP2 = false>
; __device__ __forceinline__ void gemm_phase(PG8_LAS unsigned char* lds, const Gemm g, const Sched& S, const Epi& E) {
;     ...
;             PG8_WAIT_V(8); PG8_WAIT_L(0); PG8_BAR; PG8_MMA(0, 0, At, B0); PG8_MMA(0, 1, At, B1); PG8_BAR; PG8_SCHED;
;             PG8_LDA(At, 0, 1); PG8_STAGE(PG8_SB(0, 0), b2, voffB); PG8_STAGE(PG8_SB(0, 1), b2 + hstep, voffB); PG8_STAGE(PG8_SA(0, 0), a2, voffA);
;             PG8_WAIT_V(8); PG8_WAIT_L(0); PG8_BAR; PG8_MMA(1, 0, At, B0); PG8_MMA(1, 1, At, B1); PG8_BAR; PG8_SCHED;
;             PG8_LDB(B0, 1, 0); PG8_LDB(B1, 1, 1); PG8_SCHED; PG8_LDA(At, 1, 0); PG8_STAGE(PG8_SA(0, 1), a2 + hstep, voffA);
;             PG8_WAIT_V(8); PG8_WAIT_L(0); PG8_BAR; PG8_MMA(0, 0, At, B0); PG8_MMA(0, 1, At, B1); PG8_BAR; PG8_SCHED;
	s_setprio 1
	s_waitcnt lgkmcnt(0)
	v_mfma_f32_16x16x32_bf16 v[60:63], v[136:139], v[174:177], 0
	v_mfma_f32_16x16x32_bf16 v[56:59], v[150:153], v[174:177], 0
	v_mfma_f32_16x16x32_bf16 v[44:47], v[136:139], v[182:185], 0
	v_mfma_f32_16x16x32_bf16 v[40:43], v[150:153], v[182:185], 0
	v_mfma_f32_16x16x32_bf16 v[28:31], v[136:139], v[190:193], 0
	v_mfma_f32_16x16x32_bf16 v[24:27], v[150:153], v[190:193], 0
	v_mfma_f32_16x16x32_bf16 v[12:15], v[136:139], v[202:205], 0
	v_mfma_f32_16x16x32_bf16 v[8:11], v[150:153], v[202:205], 0
	v_mfma_f32_16x16x32_bf16 v[60:63], v[146:149], v[178:181], v[60:63]
	v_mfma_f32_16x16x32_bf16 v[56:59], v[154:157], v[178:181], v[56:59]
	v_mfma_f32_16x16x32_bf16 v[44:47], v[146:149], v[186:189], v[44:47]
	v_mfma_f32_16x16x32_bf16 v[40:43], v[154:157], v[186:189], v[40:43]
	v_mfma_f32_16x16x32_bf16 v[28:31], v[146:149], v[194:197], v[28:31]
	v_mfma_f32_16x16x32_bf16 v[24:27], v[154:157], v[194:197], v[24:27]
	v_mfma_f32_16x16x32_bf16 v[12:15], v[146:149], v[206:209], v[12:15]
	v_mfma_f32_16x16x32_bf16 v[8:11], v[154:157], v[206:209], v[8:11]
	s_setprio 0
	s_setprio 1
	v_mfma_f32_16x16x32_bf16 v[52:55], v[158:161], v[174:177], 0
	v_mfma_f32_16x16x32_bf16 v[48:51], v[166:169], v[174:177], 0
	v_mfma_f32_16x16x32_bf16 v[36:39], v[158:161], v[182:185], 0
	v_mfma_f32_16x16x32_bf16 v[32:35], v[166:169], v[182:185], 0
	v_mfma_f32_16x16x32_bf16 v[20:23], v[158:161], v[190:193], 0
	v_mfma_f32_16x16x32_bf16 v[16:19], v[166:169], v[190:193], 0
	v_mfma_f32_16x16x32_bf16 v[4:7], v[158:161], v[202:205], 0
	v_mfma_f32_16x16x32_bf16 v[0:3], v[166:169], v[202:205], 0
	v_mfma_f32_16x16x32_bf16 v[52:55], v[162:165], v[178:181], v[52:55]
	v_mfma_f32_16x16x32_bf16 v[48:51], v[170:173], v[178:181], v[48:51]
	v_mfma_f32_16x16x32_bf16 v[36:39], v[162:165], v[186:189], v[36:39]
	v_mfma_f32_16x16x32_bf16 v[32:35], v[170:173], v[186:189], v[32:35]
	v_mfma_f32_16x16x32_bf16 v[20:23], v[162:165], v[194:197], v[20:23]
	v_mfma_f32_16x16x32_bf16 v[16:19], v[170:173], v[194:197], v[16:19]
	v_mfma_f32_16x16x32_bf16 v[4:7], v[162:165], v[206:209], v[4:7]
	v_mfma_f32_16x16x32_bf16 v[0:3], v[170:173], v[206:209], v[0:3]
	s_setprio 0
	s_barrier
	s_add_i32 s58, 0, 0x18000
	v_add_u32_e32 v130, s58, v142
	s_add_i32 s59, 0, 0x1c000
	ds_read_b128 v[136:139], v130
	ds_read_b128 v[146:149], v130 offset:1024
	ds_read_b128 v[150:153], v130 offset:2048
	ds_read_b128 v[154:157], v130 offset:3072
	v_add_u32_e32 v130, s59, v142
	ds_read_b128 v[158:161], v130
	ds_read_b128 v[162:165], v130 offset:1024
	ds_read_b128 v[166:169], v130 offset:2048
	ds_read_b128 v[170:173], v130 offset:3072
	s_mov_b32 m0, s41
	v_lshl_add_u64 v[212:213], v[210:211], 0, s[14:15]
	ds_read_b128 v[174:177], v145 offset:32768
	ds_read_b128 v[178:181], v145 offset:33792
	ds_read_b128 v[182:185], v145 offset:34816
	ds_read_b128 v[186:189], v145 offset:35840
	ds_read_b128 v[190:193], v145 offset:36864
	ds_read_b128 v[194:197], v145 offset:37888
	ds_read_b128 v[202:205], v145 offset:38912
	ds_read_b128 v[206:209], v145 offset:39936
	global_load_lds_dwordx4 v[212:213], off
	v_lshl_add_u64 v[212:213], v[210:211], 0, s[16:17]
	s_mov_b32 m0, s42
	s_nop 0
	global_load_lds_dwordx4 v[212:213], off
	s_waitcnt vmcnt(8)
	s_waitcnt lgkmcnt(0)
	s_barrier
	s_setprio 1
	s_waitcnt lgkmcnt(0)
	v_mfma_f32_16x16x32_bf16 v[124:127], v[136:139], v[174:177], v[124:127]
	v_mfma_f32_16x16x32_bf16 v[120:123], v[150:153], v[174:177], v[120:123]
	v_mfma_f32_16x16x32_bf16 v[108:111], v[136:139], v[182:185], v[108:111]
	v_mfma_f32_16x16x32_bf16 v[104:107], v[150:153], v[182:185], v[104:107]
	v_mfma_f32_16x16x32_bf16 v[92:95], v[136:139], v[190:193], v[92:95]
	v_mfma_f32_16x16x32_bf16 v[88:91], v[150:153], v[190:193], v[88:91]
	v_mfma_f32_16x16x32_bf16 v[76:79], v[136:139], v[202:205], v[76:79]
	v_mfma_f32_16x16x32_bf16 v[72:75], v[150:153], v[202:205], v[72:75]
	v_mfma_f32_16x16x32_bf16 v[124:127], v[146:149], v[178:181], v[124:127]
	v_mfma_f32_16x16x32_bf16 v[120:123], v[154:157], v[178:181], v[120:123]
	v_mfma_f32_16x16x32_bf16 v[108:111], v[146:149], v[186:189], v[108:111]
	v_mfma_f32_16x16x32_bf16 v[104:107], v[154:157], v[186:189], v[104:107]
	v_mfma_f32_16x16x32_bf16 v[92:95], v[146:149], v[194:197], v[92:95]
	v_mfma_f32_16x16x32_bf16 v[88:91], v[154:157], v[194:197], v[88:91]
	v_mfma_f32_16x16x32_bf16 v[76:79], v[146:149], v[206:209], v[76:79]
	v_mfma_f32_16x16x32_bf16 v[72:75], v[154:157], v[206:209], v[72:75]
	s_setprio 0
	s_setprio 1
	v_mfma_f32_16x16x32_bf16 v[116:119], v[158:161], v[174:177], v[116:119]
	v_mfma_f32_16x16x32_bf16 v[112:115], v[166:169], v[174:177], v[112:115]
	v_mfma_f32_16x16x32_bf16 v[100:103], v[158:161], v[182:185], v[100:103]
	v_mfma_f32_16x16x32_bf16 v[96:99], v[166:169], v[182:185], v[96:99]
	v_mfma_f32_16x16x32_bf16 v[84:87], v[158:161], v[190:193], v[84:87]
	v_mfma_f32_16x16x32_bf16 v[80:83], v[166:169], v[190:193], v[80:83]
	v_mfma_f32_16x16x32_bf16 v[68:71], v[158:161], v[202:205], v[68:71]
	v_mfma_f32_16x16x32_bf16 v[64:67], v[166:169], v[202:205], v[64:67]
	v_mfma_f32_16x16x32_bf16 v[116:119], v[162:165], v[178:181], v[116:119]
	v_mfma_f32_16x16x32_bf16 v[112:115], v[170:173], v[178:181], v[112:115]
	v_mfma_f32_16x16x32_bf16 v[100:103], v[162:165], v[186:189], v[100:103]
	v_mfma_f32_16x16x32_bf16 v[96:99], v[170:173], v[186:189], v[96:99]
	v_mfma_f32_16x16x32_bf16 v[84:87], v[162:165], v[194:197], v[84:87]
	v_mfma_f32_16x16x32_bf16 v[80:83], v[170:173], v[194:197], v[80:83]
	v_mfma_f32_16x16x32_bf16 v[68:71], v[162:165], v[206:209], v[68:71]
	v_mfma_f32_16x16x32_bf16 v[64:67], v[170:173], v[206:209], v[64:67]
	s_setprio 0
	s_barrier
; #define PG8_STAGE(bufoff, gbase, voff) do { _Pragma("unroll") for (int _i = 0; _i < 2; ++_i) \
;         __builtin_amdgcn_global_load_lds((const unsigned*)((const char*)(gbase) + (voff)[_i]), (PG8_LAS unsigned*)(lds + (bufoff) + ldsw + _i * 8192), 16, 0, 0); } while (0)
; #define PG8_LDA(dst, b, h) do { _Pragma("unroll") for (int m = 0; m < 4; ++m) _Pragma("unroll") for (int k = 0; k < 2; ++k) dst[m][k] = *(const PG8_LAS bf16x8*)(lds + PG8_SA(b, h) + aoff + m * 2048 + k * 1024); } while (0)
; #define PG8_LDB(dst, b, h) do { _Pragma("unroll") for (int n = 0; n < 2; ++n) _Pragma("unroll") for (int k = 0; k < 2; ++k) dst[n][k] = *(const PG8_LAS bf16x8*)(lds + PG8_SB(b, h) + boff + n * 2048 + k * 1024); } while (0)
; #define PG8_MMA(ai, bj, At, Bt) do { __builtin_amdgcn_s_setprio(1); _Pragma("unroll") for (int m = 0; m < 4; ++m) _Pragma("unroll") for (int n = 0; n < 2; ++n) _Pragma("unroll") for (int k = 0; k < 2; ++k) \
;         acc[ai][bj][m][n] = __builtin_amdgcn_mfma_f32_16x16x32_bf16(Bt[n][k], At[m][k], acc[ai][bj][m][n], 0, 0, 0); __builtin_amdgcn_s_setprio(0); } while (0)
; #define PG8_WAIT_V(n) asm volatile("s_waitcnt vmcnt(" #n ")" ::: "memory")
; #define PG8_WAIT_L(n) asm volatile("s_waitcnt lgkmcnt(" #n ")" ::: "memory")
; #define PG8_BAR __builtin_amdgcn_s_barrier()
; #define PG8_SCHED __builtin_amdgcn_sched_barrier(0)
; template <class Epi, class Sched, bool ALIGN_EPI = false, bool SP2 = false>
; __device__ __forceinline__ void gemm_phase(PG8_LAS unsigned char* lds, const Gemm g, const Sched& S, const Epi& E) {
;     ...
;         for (int t = 0; t < nt; t += 2) {
;             const bool last = (t == nt - 2);
;             const char* a1 = cA + (size_t)(t + 1) * kstep;
;             const char* a2 = last ? nA : cA + (size_t)(t + 2) * kstep; const char* b2 = last ? nB : cB + (size_t)(t + 2) * kstep;
;             const char* a3 = a2 + kstep; const char* b3 = b2 + kstep;
;             if (last && has_next) S.a_ready(nxt);
;             if constexpr (SP2) {
;             PG8_LDB(B0, 0, 0); PG8_LDB(B1, 0, 1); PG8_SCHED; PG8_LDA(At, 0, 0); PG8_STAGE(PG8_SA(1, 1), a1 + hstep, voffA);
;     ...
;             PG8_LDA(At, 1, 1); PG8_STAGE(PG8_SB(1, 0), b3, voffB); PG8_STAGE(PG8_SB(1, 1), b3 + hstep, voffB); PG8_STAGE(PG8_SA(1, 0), a3, voffA);
;             PG8_WAIT_V(8); PG8_WAIT_L(0); PG8_BAR; PG8_MMA(1, 0, At, B0); PG8_MMA(1, 1, At, B1); PG8_BAR; PG8_SCHED;
	s_add_i32 s58, s58, s38
	v_lshl_add_u64 v[212:213], v[198:199], 0, s[20:21]
	s_mov_b32 m0, s58
	ds_read_b128 v[174:177], v145 offset:49152
	ds_read_b128 v[178:181], v145 offset:50176
	ds_read_b128 v[182:185], v145 offset:51200
	ds_read_b128 v[186:189], v145 offset:52224
	ds_read_b128 v[190:193], v145 offset:53248
	ds_read_b128 v[194:197], v145 offset:54272
	ds_read_b128 v[202:205], v145 offset:55296
	ds_read_b128 v[206:209], v145 offset:56320
	global_load_lds_dwordx4 v[212:213], off
	v_lshl_add_u64 v[212:213], v[198:199], 0, s[22:23]
	s_add_i32 m0, s58, 0x2000
	s_add_i32 s58, s59, s38
	global_load_lds_dwordx4 v[212:213], off
	v_lshl_add_u64 v[212:213], v[198:199], 0, s[24:25]
	s_mov_b32 m0, s58
	v_lshl_add_u64 v[198:199], v[198:199], 0, s[26:27]
	global_load_lds_dwordx4 v[212:213], off
	s_add_i32 m0, s58, 0x2000
	s_nop 0
	global_load_lds_dwordx4 v[198:199], off
	v_lshl_add_u64 v[198:199], v[210:211], 0, s[20:21]
	s_mov_b32 m0, s46
	s_nop 0
	global_load_lds_dwordx4 v[198:199], off
	v_lshl_add_u64 v[198:199], v[210:211], 0, s[22:23]
	s_mov_b32 m0, s47
	s_nop 0
	global_load_lds_dwordx4 v[198:199], off
	s_waitcnt vmcnt(8)
	s_waitcnt lgkmcnt(0)
	s_barrier
	s_setprio 1
	s_waitcnt lgkmcnt(0)
	v_mfma_f32_16x16x32_bf16 v[60:63], v[136:139], v[174:177], v[60:63]
	v_mfma_f32_16x16x32_bf16 v[56:59], v[150:153], v[174:177], v[56:59]
	v_mfma_f32_16x16x32_bf16 v[44:47], v[136:139], v[182:185], v[44:47]
	v_mfma_f32_16x16x32_bf16 v[40:43], v[150:153], v[182:185], v[40:43]
	v_mfma_f32_16x16x32_bf16 v[28:31], v[136:139], v[190:193], v[28:31]
	v_mfma_f32_16x16x32_bf16 v[24:27], v[150:153], v[190:193], v[24:27]
	v_mfma_f32_16x16x32_bf16 v[12:15], v[136:139], v[202:205], v[12:15]
	v_mfma_f32_16x16x32_bf16 v[8:11], v[150:153], v[202:205], v[8:11]
	v_mfma_f32_16x16x32_bf16 v[60:63], v[146:149], v[178:181], v[60:63]
	v_mfma_f32_16x16x32_bf16 v[56:59], v[154:157], v[178:181], v[56:59]
	v_mfma_f32_16x16x32_bf16 v[44:47], v[146:149], v[186:189], v[44:47]
	v_mfma_f32_16x16x32_bf16 v[40:43], v[154:157], v[186:189], v[40:43]
	v_mfma_f32_16x16x32_bf16 v[28:31], v[146:149], v[194:197], v[28:31]
	v_mfma_f32_16x16x32_bf16 v[24:27], v[154:157], v[194:197], v[24:27]
	v_mfma_f32_16x16x32_bf16 v[12:15], v[146:149], v[206:209], v[12:15]
	v_mfma_f32_16x16x32_bf16 v[8:11], v[154:157], v[206:209], v[8:11]
	s_setprio 0
	s_setprio 1
	v_mfma_f32_16x16x32_bf16 v[52:55], v[158:161], v[174:177], v[52:55]
	v_mfma_f32_16x16x32_bf16 v[48:51], v[166:169], v[174:177], v[48:51]
	v_mfma_f32_16x16x32_bf16 v[36:39], v[158:161], v[182:185], v[36:39]
	v_mfma_f32_16x16x32_bf16 v[32:35], v[166:169], v[182:185], v[32:35]
	v_mfma_f32_16x16x32_bf16 v[20:23], v[158:161], v[190:193], v[20:23]
	v_mfma_f32_16x16x32_bf16 v[16:19], v[166:169], v[190:193], v[16:19]
	v_mfma_f32_16x16x32_bf16 v[4:7], v[158:161], v[202:205], v[4:7]
	v_mfma_f32_16x16x32_bf16 v[0:3], v[166:169], v[202:205], v[0:3]
	v_mfma_f32_16x16x32_bf16 v[52:55], v[162:165], v[178:181], v[52:55]
	v_mfma_f32_16x16x32_bf16 v[48:51], v[170:173], v[178:181], v[48:51]
	v_mfma_f32_16x16x32_bf16 v[36:39], v[162:165], v[186:189], v[36:39]
	v_mfma_f32_16x16x32_bf16 v[32:35], v[170:173], v[186:189], v[32:35]
	v_mfma_f32_16x16x32_bf16 v[20:23], v[162:165], v[194:197], v[20:23]
	v_mfma_f32_16x16x32_bf16 v[16:19], v[170:173], v[194:197], v[16:19]
	v_mfma_f32_16x16x32_bf16 v[4:7], v[162:165], v[206:209], v[4:7]
	v_mfma_f32_16x16x32_bf16 v[0:3], v[170:173], v[206:209], v[0:3]
	s_setprio 0
	s_barrier
	s_add_i32 s57, s57, 2
	s_add_u32 s12, s12, 0x8000
	s_addc_u32 s13, s13, 0
	s_add_u32 s36, s36, 0x8000
	s_addc_u32 s37, s37, 0
	s_and_b64 vcc, exec, s[28:29]
	s_cbranch_vccnz .LBB0_1424
	v_lshl_add_u64 v[198:199], s[12:13], 0, v[128:129]
	s_add_i32 m0, s39, 0xc000
	global_load_lds_dwordx4 v[198:199], off
	v_lshl_add_u64 v[198:199], v[198:199], 0, s[10:11]
	s_add_i32 m0, s39, 0xe000
	s_nop 0
	global_load_lds_dwordx4 v[198:199], off
.Lp5_trail:
	ds_read_b128 v[136:139], v143
	ds_read_b128 v[146:149], v143 offset:1024
	ds_read_b128 v[150:153], v143 offset:2048
	ds_read_b128 v[154:157], v143 offset:3072
	ds_read_b128 v[158:161], v144
	ds_read_b128 v[162:165], v144 offset:1024
	ds_read_b128 v[166:169], v144 offset:2048
	ds_read_b128 v[170:173], v144 offset:3072
	s_add_u32 s58, s12, 0xfff54000
	s_addc_u32 s59, s13, -1
	s_cmp_eq_u32 s57, 40
	s_cselect_b32 s59, s3, s59
	s_cselect_b32 s58, s2, s58
	s_cselect_b32 s61, s35, s37
	s_cselect_b32 s60, s34, s36
	ds_read_b128 v[174:177], v145
	ds_read_b128 v[178:181], v145 offset:1024
	ds_read_b128 v[182:185], v145 offset:2048
	ds_read_b128 v[186:189], v145 offset:3072
	ds_read_b128 v[190:193], v145 offset:4096
	ds_read_b128 v[194:197], v145 offset:5120
	ds_read_b128 v[202:205], v145 offset:6144
	ds_read_b128 v[206:209], v145 offset:7168
	s_waitcnt vmcnt(8)
	s_waitcnt lgkmcnt(0)
	s_barrier
; #define PG8_STAGE(bufoff, gbase, voff) do { _Pragma("unroll") for (int _i = 0; _i < 2; ++_i) \
;         __builtin_amdgcn_global_load_lds((const unsigned*)((const char*)(gbase) + (voff)[_i]), (PG8_LAS unsigned*)(lds + (bufoff) + ldsw + _i * 8192), 16, 0, 0); } while (0)
; #define PG8_LDA(dst, b, h) do { _Pragma("unroll") for (int m = 0; m < 4; ++m) _Pragma("unroll") for (int k = 0; k < 2; ++k) dst[m][k] = *(const PG8_LAS bf16x8*)(lds + PG8_SA(b, h) + aoff + m * 2048 + k * 1024); } while (0)
; #define PG8_LDB(dst, b, h) do { _Pragma("unroll") for (int n = 0; n < 2; ++n) _Pragma("unroll") for (int k = 0; k < 2; ++k) dst[n][k] = *(const PG8_LAS bf16x8*)(lds + PG8_SB(b, h) + boff + n * 2048 + k * 1024); } while (0)
; #define PG8_MMA(ai, bj, At, Bt) do { __builtin_amdgcn_s_setprio(1); _Pragma("unroll") for (int m = 0; m < 4; ++m) _Pragma("unroll") for (int n = 0; n < 2; ++n) _Pragma("unroll") for (int k = 0; k < 2; ++k) \
;         acc[ai][bj][m][n] = __builtin_amdgcn_mfma_f32_16x16x32_bf16(Bt[n][k], At[m][k], acc[ai][bj][m][n], 0, 0, 0); __builtin_amdgcn_s_setprio(0); } while (0)
; #define PG8_WAIT_V(n) asm volatile("s_waitcnt vmcnt(" #n ")" ::: "memory")
; #define PG8_WAIT_L(n) asm volatile("s_waitcnt lgkmcnt(" #n ")" ::: "memory")
; #define PG8_BAR __builtin_amdgcn_s_barrier()
; #define PG8_SCHED __builtin_amdgcn_sched_barrier(0)
; template <class Epi, class Sched, bool ALIGN_EPI = false, bool SP2 = false>
; __device__ __forceinline__ void gemm_phase(PG8_LAS unsigned char* lds, const Gemm g, const Sched& S, const Epi& E) {
;     ...
;             PG8_LDB(B0, 0, 0); PG8_LDB(B1, 0, 1); PG8_SCHED; PG8_LDA(At, 0, 0); PG8_STAGE(PG8_SA(1, 1), a1 + hstep, voffA);
;             PG8_WAIT_V(8); PG8_WAIT_L(0); PG8_BAR; PG8_MMA(0, 0, At, B0); PG8_MMA(0, 1, At, B1); PG8_BAR; PG8_SCHED;
;             PG8_LDA(At, 0, 1); PG8_STAGE(PG8_SB(0, 0), b2, voffB); PG8_STAGE(PG8_SB(0, 1), b2 + hstep, voffB); PG8_STAGE(PG8_SA(0, 0), a2, voffA);
;             PG8_WAIT_V(8); PG8_WAIT_L(0); PG8_BAR; PG8_MMA(1, 0, At, B0); PG8_MMA(1, 1, At, B1); PG8_BAR; PG8_SCHED;
	s_setprio 1
	s_waitcnt lgkmcnt(0)
	v_mfma_f32_16x16x32_bf16 v[124:127], v[136:139], v[174:177], v[124:127]
	v_lshl_add_u64 v[198:199], s[60:61], 0, v[128:129]
	v_mfma_f32_16x16x32_bf16 v[120:123], v[150:153], v[174:177], v[120:123]
	s_add_i32 s60, s51, s38
	v_mfma_f32_16x16x32_bf16 v[108:111], v[136:139], v[182:185], v[108:111]
	s_mov_b32 m0, s60
	v_mfma_f32_16x16x32_bf16 v[104:107], v[150:153], v[182:185], v[104:107]
	global_load_lds_dwordx4 v[198:199], off
	v_mfma_f32_16x16x32_bf16 v[92:95], v[136:139], v[190:193], v[92:95]
	v_lshl_add_u64 v[210:211], v[198:199], 0, s[10:11]
	v_mfma_f32_16x16x32_bf16 v[88:91], v[150:153], v[190:193], v[88:91]
	s_add_i32 m0, s60, 0x2000
	v_mfma_f32_16x16x32_bf16 v[76:79], v[136:139], v[202:205], v[76:79]
	s_add_i32 s60, s52, s38
	v_mfma_f32_16x16x32_bf16 v[72:75], v[150:153], v[202:205], v[72:75]
	global_load_lds_dwordx4 v[210:211], off
	v_mfma_f32_16x16x32_bf16 v[124:127], v[146:149], v[178:181], v[124:127]
	v_lshl_add_u64 v[210:211], v[198:199], 0, s[14:15]
	v_mfma_f32_16x16x32_bf16 v[120:123], v[154:157], v[178:181], v[120:123]
	s_mov_b32 m0, s60
	v_mfma_f32_16x16x32_bf16 v[108:111], v[146:149], v[186:189], v[108:111]
	global_load_lds_dwordx4 v[210:211], off
	v_mfma_f32_16x16x32_bf16 v[104:107], v[154:157], v[186:189], v[104:107]
	v_lshl_add_u64 v[210:211], v[198:199], 0, s[16:17]
	v_mfma_f32_16x16x32_bf16 v[92:95], v[146:149], v[194:197], v[92:95]
	s_add_i32 m0, s60, 0x2000
	v_mfma_f32_16x16x32_bf16 v[88:91], v[154:157], v[194:197], v[88:91]
	global_load_lds_dwordx4 v[210:211], off
	v_mfma_f32_16x16x32_bf16 v[76:79], v[146:149], v[206:209], v[76:79]
	v_lshl_add_u64 v[210:211], s[58:59], 0, v[128:129]
	v_mfma_f32_16x16x32_bf16 v[72:75], v[154:157], v[206:209], v[72:75]
	s_mov_b32 m0, s39
	s_setprio 0
	s_setprio 1
	v_mfma_f32_16x16x32_bf16 v[116:119], v[158:161], v[174:177], v[116:119]
	v_lshl_add_u64 v[212:213], v[210:211], 0, s[10:11]
	v_mfma_f32_16x16x32_bf16 v[112:115], v[166:169], v[174:177], v[112:115]
	global_load_lds_dwordx4 v[210:211], off
	v_mfma_f32_16x16x32_bf16 v[100:103], v[158:161], v[182:185], v[100:103]
	s_mov_b32 m0, s40
	v_mfma_f32_16x16x32_bf16 v[96:99], v[166:169], v[182:185], v[96:99]
	global_load_lds_dwordx4 v[212:213], off
	v_mfma_f32_16x16x32_bf16 v[84:87], v[158:161], v[190:193], v[84:87]
	v_mfma_f32_16x16x32_bf16 v[80:83], v[166:169], v[190:193], v[80:83]
	v_mfma_f32_16x16x32_bf16 v[68:71], v[158:161], v[202:205], v[68:71]
	v_mfma_f32_16x16x32_bf16 v[64:67], v[166:169], v[202:205], v[64:67]
	v_mfma_f32_16x16x32_bf16 v[116:119], v[162:165], v[178:181], v[116:119]
	v_mfma_f32_16x16x32_bf16 v[112:115], v[170:173], v[178:181], v[112:115]
	v_mfma_f32_16x16x32_bf16 v[100:103], v[162:165], v[186:189], v[100:103]
	v_mfma_f32_16x16x32_bf16 v[96:99], v[170:173], v[186:189], v[96:99]
	v_mfma_f32_16x16x32_bf16 v[84:87], v[162:165], v[194:197], v[84:87]
	v_mfma_f32_16x16x32_bf16 v[80:83], v[170:173], v[194:197], v[80:83]
	v_mfma_f32_16x16x32_bf16 v[68:71], v[162:165], v[206:209], v[68:71]
	v_mfma_f32_16x16x32_bf16 v[64:67], v[170:173], v[206:209], v[64:67]
	s_setprio 0
	s_barrier
	ds_read_b128 v[174:177], v145 offset:16384
	ds_read_b128 v[178:181], v145 offset:17408
	ds_read_b128 v[182:185], v145 offset:18432
	ds_read_b128 v[186:189], v145 offset:19456
	ds_read_b128 v[190:193], v145 offset:20480
	ds_read_b128 v[194:197], v145 offset:21504
	ds_read_b128 v[202:205], v145 offset:22528
	ds_read_b128 v[206:209], v145 offset:23552
	s_waitcnt vmcnt(8)
	s_waitcnt lgkmcnt(0)
	s_barrier
	s_setprio 1
	s_waitcnt lgkmcnt(0)
	v_mfma_f32_16x16x32_bf16 v[60:63], v[136:139], v[174:177], v[60:63]
	s_mov_b32 m0, s41
	v_mfma_f32_16x16x32_bf16 v[56:59], v[150:153], v[174:177], v[56:59]
	v_lshl_add_u64 v[212:213], v[210:211], 0, s[14:15]
	v_mfma_f32_16x16x32_bf16 v[44:47], v[136:139], v[182:185], v[44:47]
	global_load_lds_dwordx4 v[212:213], off
	v_mfma_f32_16x16x32_bf16 v[40:43], v[150:153], v[182:185], v[40:43]
	v_lshl_add_u64 v[212:213], v[210:211], 0, s[16:17]
	v_mfma_f32_16x16x32_bf16 v[28:31], v[136:139], v[190:193], v[28:31]
	s_mov_b32 m0, s42
	v_mfma_f32_16x16x32_bf16 v[24:27], v[150:153], v[190:193], v[24:27]
	global_load_lds_dwordx4 v[212:213], off
	v_mfma_f32_16x16x32_bf16 v[12:15], v[136:139], v[202:205], v[12:15]
	v_mfma_f32_16x16x32_bf16 v[8:11], v[150:153], v[202:205], v[8:11]
	v_mfma_f32_16x16x32_bf16 v[60:63], v[146:149], v[178:181], v[60:63]
	v_mfma_f32_16x16x32_bf16 v[56:59], v[154:157], v[178:181], v[56:59]
	v_mfma_f32_16x16x32_bf16 v[44:47], v[146:149], v[186:189], v[44:47]
	v_mfma_f32_16x16x32_bf16 v[40:43], v[154:157], v[186:189], v[40:43]
	v_mfma_f32_16x16x32_bf16 v[28:31], v[146:149], v[194:197], v[28:31]
	v_mfma_f32_16x16x32_bf16 v[24:27], v[154:157], v[194:197], v[24:27]
	v_mfma_f32_16x16x32_bf16 v[12:15], v[146:149], v[206:209], v[12:15]
	v_mfma_f32_16x16x32_bf16 v[8:11], v[154:157], v[206:209], v[8:11]
	s_setprio 0
	s_setprio 1
	v_mfma_f32_16x16x32_bf16 v[52:55], v[158:161], v[174:177], v[52:55]
	v_mfma_f32_16x16x32_bf16 v[48:51], v[166:169], v[174:177], v[48:51]
	v_mfma_f32_16x16x32_bf16 v[36:39], v[158:161], v[182:185], v[36:39]
	v_mfma_f32_16x16x32_bf16 v[32:35], v[166:169], v[182:185], v[32:35]
	v_mfma_f32_16x16x32_bf16 v[20:23], v[158:161], v[190:193], v[20:23]
	v_mfma_f32_16x16x32_bf16 v[16:19], v[166:169], v[190:193], v[16:19]
	v_mfma_f32_16x16x32_bf16 v[4:7], v[158:161], v[202:205], v[4:7]
	v_mfma_f32_16x16x32_bf16 v[0:3], v[166:169], v[202:205], v[0:3]
	v_mfma_f32_16x16x32_bf16 v[52:55], v[162:165], v[178:181], v[52:55]
	v_mfma_f32_16x16x32_bf16 v[48:51], v[170:173], v[178:181], v[48:51]
	v_mfma_f32_16x16x32_bf16 v[36:39], v[162:165], v[186:189], v[36:39]
	v_mfma_f32_16x16x32_bf16 v[32:35], v[170:173], v[186:189], v[32:35]
	v_mfma_f32_16x16x32_bf16 v[20:23], v[162:165], v[194:197], v[20:23]
	v_mfma_f32_16x16x32_bf16 v[16:19], v[170:173], v[194:197], v[16:19]
	v_mfma_f32_16x16x32_bf16 v[4:7], v[162:165], v[206:209], v[4:7]
	v_mfma_f32_16x16x32_bf16 v[0:3], v[170:173], v[206:209], v[0:3]
	s_setprio 0
	s_barrier
; #define PG8_STAGE(bufoff, gbase, voff) do { _Pragma("unroll") for (int _i = 0; _i < 2; ++_i) \
;         __builtin_amdgcn_global_load_lds((const unsigned*)((const char*)(gbase) + (voff)[_i]), (PG8_LAS unsigned*)(lds + (bufoff) + ldsw + _i * 8192), 16, 0, 0); } while (0)
; #define PG8_LDA(dst, b, h) do { _Pragma("unroll") for (int m = 0; m < 4; ++m) _Pragma("unroll") for (int k = 0; k < 2; ++k) dst[m][k] = *(const PG8_LAS bf16x8*)(lds + PG8_SA(b, h) + aoff + m * 2048 + k * 1024); } while (0)
; #define PG8_LDB(dst, b, h) do { _Pragma("unroll") for (int n = 0; n < 2; ++n) _Pragma("unroll") for (int k = 0; k < 2; ++k) dst[n][k] = *(const PG8_LAS bf16x8*)(lds + PG8_SB(b, h) + boff + n * 2048 + k * 1024); } while (0)
; #define PG8_MMA(ai, bj, At, Bt) do { __builtin_amdgcn_s_setprio(1); _Pragma("unroll") for (int m = 0; m < 4; ++m) _Pragma("unroll") for (int n = 0; n < 2; ++n) _Pragma("unroll") for (int k = 0; k < 2; ++k) \
;         acc[ai][bj][m][n] = __builtin_amdgcn_mfma_f32_16x16x32_bf16(Bt[n][k], At[m][k], acc[ai][bj][m][n], 0, 0, 0); __builtin_amdgcn_s_setprio(0); } while (0)
; #define PG8_WAIT_V(n) asm volatile("s_waitcnt vmcnt(" #n ")" ::: "memory")
; #define PG8_WAIT_L(n) asm volatile("s_waitcnt lgkmcnt(" #n ")" ::: "memory")
; #define PG8_BAR __builtin_amdgcn_s_barrier()
; #define PG8_SCHED __builtin_amdgcn_sched_barrier(0)
; template <class Epi, class Sched, bool ALIGN_EPI = false, bool SP2 = false>
; __device__ __forceinline__ void gemm_phase(PG8_LAS unsigned char* lds, const Gemm g, const Sched& S, const Epi& E) {
;     ...
;             PG8_LDB(B0, 1, 0); PG8_LDB(B1, 1, 1); PG8_SCHED; PG8_LDA(At, 1, 0); PG8_STAGE(PG8_SA(0, 1), a2 + hstep, voffA);
;             PG8_WAIT_V(8); PG8_WAIT_L(0); PG8_BAR; PG8_MMA(0, 0, At, B0); PG8_MMA(0, 1, At, B1); PG8_BAR; PG8_SCHED;
;             PG8_LDA(At, 1, 1); PG8_STAGE(PG8_SB(1, 0), b3, voffB); PG8_STAGE(PG8_SB(1, 1), b3 + hstep, voffB); PG8_STAGE(PG8_SA(1, 0), a3, voffA);
;             PG8_WAIT_V(8); PG8_WAIT_L(0); PG8_BAR; PG8_MMA(1, 0, At, B0); PG8_MMA(1, 1, At, B1); PG8_BAR; PG8_SCHED;
	s_add_i32 s58, 0, 0x18000
	v_add_u32_e32 v130, s58, v142
	s_add_i32 s59, 0, 0x1c000
	ds_read_b128 v[136:139], v130
	ds_read_b128 v[146:149], v130 offset:1024
	ds_read_b128 v[150:153], v130 offset:2048
	ds_read_b128 v[154:157], v130 offset:3072
	v_add_u32_e32 v130, s59, v142
	ds_read_b128 v[158:161], v130
	ds_read_b128 v[162:165], v130 offset:1024
	ds_read_b128 v[166:169], v130 offset:2048
	ds_read_b128 v[170:173], v130 offset:3072
	ds_read_b128 v[174:177], v145 offset:32768
	ds_read_b128 v[178:181], v145 offset:33792
	ds_read_b128 v[182:185], v145 offset:34816
	ds_read_b128 v[186:189], v145 offset:35840
	ds_read_b128 v[190:193], v145 offset:36864
	ds_read_b128 v[194:197], v145 offset:37888
	ds_read_b128 v[202:205], v145 offset:38912
	ds_read_b128 v[206:209], v145 offset:39936
	s_waitcnt vmcnt(8)
	s_waitcnt lgkmcnt(0)
	s_barrier
	s_setprio 1
	s_waitcnt lgkmcnt(0)
	v_mfma_f32_16x16x32_bf16 v[124:127], v[136:139], v[174:177], v[124:127]
	s_add_i32 s58, s58, s38
	v_mfma_f32_16x16x32_bf16 v[120:123], v[150:153], v[174:177], v[120:123]
	v_lshl_add_u64 v[212:213], v[198:199], 0, s[20:21]
	v_mfma_f32_16x16x32_bf16 v[108:111], v[136:139], v[182:185], v[108:111]
	s_mov_b32 m0, s58
	v_mfma_f32_16x16x32_bf16 v[104:107], v[150:153], v[182:185], v[104:107]
	global_load_lds_dwordx4 v[212:213], off
	v_mfma_f32_16x16x32_bf16 v[92:95], v[136:139], v[190:193], v[92:95]
	v_lshl_add_u64 v[212:213], v[198:199], 0, s[22:23]
	v_mfma_f32_16x16x32_bf16 v[88:91], v[150:153], v[190:193], v[88:91]
	s_add_i32 m0, s58, 0x2000
	v_mfma_f32_16x16x32_bf16 v[76:79], v[136:139], v[202:205], v[76:79]
	s_add_i32 s58, s59, s38
	v_mfma_f32_16x16x32_bf16 v[72:75], v[150:153], v[202:205], v[72:75]
	global_load_lds_dwordx4 v[212:213], off
	v_mfma_f32_16x16x32_bf16 v[124:127], v[146:149], v[178:181], v[124:127]
	v_lshl_add_u64 v[212:213], v[198:199], 0, s[24:25]
	v_mfma_f32_16x16x32_bf16 v[120:123], v[154:157], v[178:181], v[120:123]
	s_mov_b32 m0, s58
	v_mfma_f32_16x16x32_bf16 v[108:111], v[146:149], v[186:189], v[108:111]
	v_lshl_add_u64 v[198:199], v[198:199], 0, s[26:27]
	v_mfma_f32_16x16x32_bf16 v[104:107], v[154:157], v[186:189], v[104:107]
	global_load_lds_dwordx4 v[212:213], off
	v_mfma_f32_16x16x32_bf16 v[92:95], v[146:149], v[194:197], v[92:95]
	s_add_i32 m0, s58, 0x2000
	v_mfma_f32_16x16x32_bf16 v[88:91], v[154:157], v[194:197], v[88:91]
	global_load_lds_dwordx4 v[198:199], off
	v_mfma_f32_16x16x32_bf16 v[76:79], v[146:149], v[206:209], v[76:79]
	v_lshl_add_u64 v[198:199], v[210:211], 0, s[20:21]
	v_mfma_f32_16x16x32_bf16 v[72:75], v[154:157], v[206:209], v[72:75]
	s_mov_b32 m0, s46
	s_setprio 0
	s_setprio 1
	v_mfma_f32_16x16x32_bf16 v[116:119], v[158:161], v[174:177], v[116:119]
	global_load_lds_dwordx4 v[198:199], off
	v_mfma_f32_16x16x32_bf16 v[112:115], v[166:169], v[174:177], v[112:115]
	v_lshl_add_u64 v[198:199], v[210:211], 0, s[22:23]
	v_mfma_f32_16x16x32_bf16 v[100:103], v[158:161], v[182:185], v[100:103]
	s_mov_b32 m0, s47
	v_mfma_f32_16x16x32_bf16 v[96:99], v[166:169], v[182:185], v[96:99]
	global_load_lds_dwordx4 v[198:199], off
	v_mfma_f32_16x16x32_bf16 v[84:87], v[158:161], v[190:193], v[84:87]
	v_mfma_f32_16x16x32_bf16 v[80:83], v[166:169], v[190:193], v[80:83]
	v_mfma_f32_16x16x32_bf16 v[68:71], v[158:161], v[202:205], v[68:71]
	v_mfma_f32_16x16x32_bf16 v[64:67], v[166:169], v[202:205], v[64:67]
	v_mfma_f32_16x16x32_bf16 v[116:119], v[162:165], v[178:181], v[116:119]
	v_mfma_f32_16x16x32_bf16 v[112:115], v[170:173], v[178:181], v[112:115]
	v_mfma_f32_16x16x32_bf16 v[100:103], v[162:165], v[186:189], v[100:103]
	v_mfma_f32_16x16x32_bf16 v[96:99], v[170:173], v[186:189], v[96:99]
	v_mfma_f32_16x16x32_bf16 v[84:87], v[162:165], v[194:197], v[84:87]
	v_mfma_f32_16x16x32_bf16 v[80:83], v[170:173], v[194:197], v[80:83]
	v_mfma_f32_16x16x32_bf16 v[68:71], v[162:165], v[206:209], v[68:71]
	v_mfma_f32_16x16x32_bf16 v[64:67], v[170:173], v[206:209], v[64:67]
	s_setprio 0
	s_barrier
	ds_read_b128 v[174:177], v145 offset:49152
	ds_read_b128 v[178:181], v145 offset:50176
	ds_read_b128 v[182:185], v145 offset:51200
	ds_read_b128 v[186:189], v145 offset:52224
	ds_read_b128 v[190:193], v145 offset:53248
	ds_read_b128 v[194:197], v145 offset:54272
	ds_read_b128 v[202:205], v145 offset:55296
	ds_read_b128 v[206:209], v145 offset:56320
	s_waitcnt vmcnt(8)
	s_waitcnt lgkmcnt(0)
	s_barrier
	s_setprio 1
	s_waitcnt lgkmcnt(0)
	v_mfma_f32_16x16x32_bf16 v[60:63], v[136:139], v[174:177], v[60:63]
	s_add_u32 s12, s12, 0x8000
	s_addc_u32 s13, s13, 0
	s_cmp_eq_u32 s57, 40
	s_cbranch_scc1 .Lp5_tskip
	v_lshl_add_u64 v[198:199], s[12:13], 0, v[128:129]
	s_add_i32 m0, s39, 0xc000
	global_load_lds_dwordx4 v[198:199], off
	v_lshl_add_u64 v[198:199], v[198:199], 0, s[10:11]
	s_add_i32 m0, s39, 0xe000
	s_nop 0
	global_load_lds_dwordx4 v[198:199], off
; #define PG8_STAGE(bufoff, gbase, voff) do { _Pragma("unroll") for (int _i = 0; _i < 2; ++_i) \
;         __builtin_amdgcn_global_load_lds((const unsigned*)((const char*)(gbase) + (voff)[_i]), (PG8_LAS unsigned*)(lds + (bufoff) + ldsw + _i * 8192), 16, 0, 0); } while (0)
; #define PG8_LDA(dst, b, h) do { _Pragma("unroll") for (int m = 0; m < 4; ++m) _Pragma("unroll") for (int k = 0; k < 2; ++k) dst[m][k] = *(const PG8_LAS bf16x8*)(lds + PG8_SA(b, h) + aoff + m * 2048 + k * 1024); } while (0)
; #define PG8_LDB(dst, b, h) do { _Pragma("unroll") for (int n = 0; n < 2; ++n) _Pragma("unroll") for (int k = 0; k < 2; ++k) dst[n][k] = *(const PG8_LAS bf16x8*)(lds + PG8_SB(b, h) + boff + n * 2048 + k * 1024); } while (0)
; #define PG8_MMA(ai, bj, At, Bt) do { __builtin_amdgcn_s_setprio(1); _Pragma("unroll") for (int m = 0; m < 4; ++m) _Pragma("unroll") for (int n = 0; n < 2; ++n) _Pragma("unroll") for (int k = 0; k < 2; ++k) \
;         acc[ai][bj][m][n] = __builtin_amdgcn_mfma_f32_16x16x32_bf16(Bt[n][k], At[m][k], acc[ai][bj][m][n], 0, 0, 0); __builtin_amdgcn_s_setprio(0); } while (0)
; #define PG8_WAIT_V(n) asm volatile("s_waitcnt vmcnt(" #n ")" ::: "memory")
; #define PG8_WAIT_L(n) asm volatile("s_waitcnt lgkmcnt(" #n ")" ::: "memory")
; #define PG8_BAR __builtin_amdgcn_s_barrier()
; #define PG8_SCHED __builtin_amdgcn_sched_barrier(0)
; template <class Epi, class Sched, bool ALIGN_EPI = false, bool SP2 = false>
; __device__ __forceinline__ void gemm_phase(PG8_LAS unsigned char* lds, const Gemm g, const Sched& S, const Epi& E) {
;     ...
;             PG8_LDB(B0, 0, 0); PG8_LDB(B1, 0, 1); PG8_SCHED; PG8_LDA(At, 0, 0); PG8_STAGE(PG8_SA(1, 1), a1 + hstep, voffA);
;             PG8_WAIT_V(8); PG8_WAIT_L(0); PG8_BAR; PG8_MMA(0, 0, At, B0); PG8_MMA(0, 1, At, B1); PG8_BAR; PG8_SCHED;
;     ...
;             PG8_LDA(At, 1, 1); PG8_STAGE(PG8_SB(1, 0), b3, voffB); PG8_STAGE(PG8_SB(1, 1), b3 + hstep, voffB); PG8_STAGE(PG8_SA(1, 0), a3, voffA);
;             PG8_WAIT_V(8); PG8_WAIT_L(0); PG8_BAR; PG8_MMA(1, 0, At, B0); PG8_MMA(1, 1, At, B1); PG8_BAR; PG8_SCHED;
.Lp5_tskip:
	v_mfma_f32_16x16x32_bf16 v[56:59], v[150:153], v[174:177], v[56:59]
	v_mfma_f32_16x16x32_bf16 v[44:47], v[136:139], v[182:185], v[44:47]
	v_mfma_f32_16x16x32_bf16 v[40:43], v[150:153], v[182:185], v[40:43]
	v_mfma_f32_16x16x32_bf16 v[28:31], v[136:139], v[190:193], v[28:31]
	v_mfma_f32_16x16x32_bf16 v[24:27], v[150:153], v[190:193], v[24:27]
	v_mfma_f32_16x16x32_bf16 v[12:15], v[136:139], v[202:205], v[12:15]
	v_mfma_f32_16x16x32_bf16 v[8:11], v[150:153], v[202:205], v[8:11]
	v_mfma_f32_16x16x32_bf16 v[60:63], v[146:149], v[178:181], v[60:63]
	v_mfma_f32_16x16x32_bf16 v[56:59], v[154:157], v[178:181], v[56:59]
	v_mfma_f32_16x16x32_bf16 v[44:47], v[146:149], v[186:189], v[44:47]
	v_mfma_f32_16x16x32_bf16 v[40:43], v[154:157], v[186:189], v[40:43]
	v_mfma_f32_16x16x32_bf16 v[28:31], v[146:149], v[194:197], v[28:31]
	v_mfma_f32_16x16x32_bf16 v[24:27], v[154:157], v[194:197], v[24:27]
	v_mfma_f32_16x16x32_bf16 v[12:15], v[146:149], v[206:209], v[12:15]
	v_mfma_f32_16x16x32_bf16 v[8:11], v[154:157], v[206:209], v[8:11]
	s_setprio 0
	s_setprio 1
	v_mfma_f32_16x16x32_bf16 v[52:55], v[158:161], v[174:177], v[52:55]
	v_mfma_f32_16x16x32_bf16 v[48:51], v[166:169], v[174:177], v[48:51]
	v_mfma_f32_16x16x32_bf16 v[36:39], v[158:161], v[182:185], v[36:39]
	v_mfma_f32_16x16x32_bf16 v[32:35], v[166:169], v[182:185], v[32:35]
	v_mfma_f32_16x16x32_bf16 v[20:23], v[158:161], v[190:193], v[20:23]
	v_mfma_f32_16x16x32_bf16 v[16:19], v[166:169], v[190:193], v[16:19]
	v_mfma_f32_16x16x32_bf16 v[4:7], v[158:161], v[202:205], v[4:7]
	v_mfma_f32_16x16x32_bf16 v[0:3], v[166:169], v[202:205], v[0:3]
	v_mfma_f32_16x16x32_bf16 v[52:55], v[162:165], v[178:181], v[52:55]
	v_mfma_f32_16x16x32_bf16 v[48:51], v[170:173], v[178:181], v[48:51]
	v_mfma_f32_16x16x32_bf16 v[36:39], v[162:165], v[186:189], v[36:39]
	v_mfma_f32_16x16x32_bf16 v[32:35], v[170:173], v[186:189], v[32:35]
	v_mfma_f32_16x16x32_bf16 v[20:23], v[162:165], v[194:197], v[20:23]
	v_mfma_f32_16x16x32_bf16 v[16:19], v[170:173], v[194:197], v[16:19]
	v_mfma_f32_16x16x32_bf16 v[4:7], v[162:165], v[206:209], v[4:7]
	v_mfma_f32_16x16x32_bf16 v[0:3], v[170:173], v[206:209], v[0:3]
	s_setprio 0
	s_barrier
	s_add_i32 s57, s57, 2
	s_add_u32 s36, s36, 0x8000
	s_addc_u32 s37, s37, 0
	s_cmp_gt_u32 s57, 41
	s_cbranch_scc0 .Lp5_trail
	s_branch .Lp5_done
.LBB0_1424:
	ds_read_b128 v[136:139], v143
	ds_read_b128 v[146:149], v143 offset:1024
	ds_read_b128 v[150:153], v143 offset:2048
	ds_read_b128 v[154:157], v143 offset:3072
	ds_read_b128 v[158:161], v144
	ds_read_b128 v[162:165], v144 offset:1024
	ds_read_b128 v[166:169], v144 offset:2048
	ds_read_b128 v[170:173], v144 offset:3072
	s_add_u32 s58, s12, 0xfff54000
	s_addc_u32 s59, s13, -1
	s_cmp_eq_u32 s57, 40
	s_cselect_b32 s59, s3, s59
	s_cselect_b32 s58, s2, s58
	s_cselect_b32 s61, s35, s37
	s_cselect_b32 s60, s34, s36
	v_lshl_add_u64 v[198:199], s[12:13], 0, v[128:129]
	s_add_i32 m0, s39, 0xc000
	ds_read_b128 v[174:177], v145
	ds_read_b128 v[178:181], v145 offset:1024
	ds_read_b128 v[182:185], v145 offset:2048
	ds_read_b128 v[186:189], v145 offset:3072
	ds_read_b128 v[190:193], v145 offset:4096
	ds_read_b128 v[194:197], v145 offset:5120
	ds_read_b128 v[202:205], v145 offset:6144
	ds_read_b128 v[206:209], v145 offset:7168
	global_load_lds_dwordx4 v[198:199], off
	v_lshl_add_u64 v[198:199], v[198:199], 0, s[10:11]
	s_add_i32 m0, s39, 0xe000
	s_nop 0
	global_load_lds_dwordx4 v[198:199], off
	s_waitcnt lgkmcnt(0)
	s_barrier
	s_setprio 1
	s_waitcnt lgkmcnt(0)
	v_mfma_f32_16x16x32_bf16 v[124:127], v[136:139], v[174:177], v[124:127]
	v_mfma_f32_16x16x32_bf16 v[120:123], v[150:153], v[174:177], v[120:123]
	v_mfma_f32_16x16x32_bf16 v[108:111], v[136:139], v[182:185], v[108:111]
	v_mfma_f32_16x16x32_bf16 v[104:107], v[150:153], v[182:185], v[104:107]
	v_mfma_f32_16x16x32_bf16 v[92:95], v[136:139], v[190:193], v[92:95]
	v_mfma_f32_16x16x32_bf16 v[88:91], v[150:153], v[190:193], v[88:91]
	v_mfma_f32_16x16x32_bf16 v[76:79], v[136:139], v[202:205], v[76:79]
	v_mfma_f32_16x16x32_bf16 v[72:75], v[150:153], v[202:205], v[72:75]
	v_mfma_f32_16x16x32_bf16 v[124:127], v[146:149], v[178:181], v[124:127]
	v_mfma_f32_16x16x32_bf16 v[120:123], v[154:157], v[178:181], v[120:123]
	v_mfma_f32_16x16x32_bf16 v[108:111], v[146:149], v[186:189], v[108:111]
	v_mfma_f32_16x16x32_bf16 v[104:107], v[154:157], v[186:189], v[104:107]
	v_mfma_f32_16x16x32_bf16 v[92:95], v[146:149], v[194:197], v[92:95]
	v_mfma_f32_16x16x32_bf16 v[88:91], v[154:157], v[194:197], v[88:91]
	v_mfma_f32_16x16x32_bf16 v[76:79], v[146:149], v[206:209], v[76:79]
	v_mfma_f32_16x16x32_bf16 v[72:75], v[154:157], v[206:209], v[72:75]
	s_setprio 0
	s_setprio 1
	v_mfma_f32_16x16x32_bf16 v[116:119], v[158:161], v[174:177], v[116:119]
	v_mfma_f32_16x16x32_bf16 v[112:115], v[166:169], v[174:177], v[112:115]
	v_mfma_f32_16x16x32_bf16 v[100:103], v[158:161], v[182:185], v[100:103]
	v_mfma_f32_16x16x32_bf16 v[96:99], v[166:169], v[182:185], v[96:99]
	v_mfma_f32_16x16x32_bf16 v[84:87], v[158:161], v[190:193], v[84:87]
	v_mfma_f32_16x16x32_bf16 v[80:83], v[166:169], v[190:193], v[80:83]
	v_mfma_f32_16x16x32_bf16 v[68:71], v[158:161], v[202:205], v[68:71]
	v_mfma_f32_16x16x32_bf16 v[64:67], v[166:169], v[202:205], v[64:67]
	v_mfma_f32_16x16x32_bf16 v[116:119], v[162:165], v[178:181], v[116:119]
	v_mfma_f32_16x16x32_bf16 v[112:115], v[170:173], v[178:181], v[112:115]
	v_mfma_f32_16x16x32_bf16 v[100:103], v[162:165], v[186:189], v[100:103]
	v_mfma_f32_16x16x32_bf16 v[96:99], v[170:173], v[186:189], v[96:99]
	v_mfma_f32_16x16x32_bf16 v[84:87], v[162:165], v[194:197], v[84:87]
	v_mfma_f32_16x16x32_bf16 v[80:83], v[170:173], v[194:197], v[80:83]
	v_mfma_f32_16x16x32_bf16 v[68:71], v[162:165], v[206:209], v[68:71]
	v_mfma_f32_16x16x32_bf16 v[64:67], v[170:173], v[206:209], v[64:67]
	s_setprio 0
	s_waitcnt vmcnt(8)
	s_barrier
; #define PG8_STAGE(bufoff, gbase, voff) do { _Pragma("unroll") for (int _i = 0; _i < 2; ++_i) \
;         __builtin_amdgcn_global_load_lds((const unsigned*)((const char*)(gbase) + (voff)[_i]), (PG8_LAS unsigned*)(lds + (bufoff) + ldsw + _i * 8192), 16, 0, 0); } while (0)
; #define PG8_LDA(dst, b, h) do { _Pragma("unroll") for (int m = 0; m < 4; ++m) _Pragma("unroll") for (int k = 0; k < 2; ++k) dst[m][k] = *(const PG8_LAS bf16x8*)(lds + PG8_SA(b, h) + aoff + m * 2048 + k * 1024); } while (0)
; #define PG8_LDB(dst, b, h) do { _Pragma("unroll") for (int n = 0; n < 2; ++n) _Pragma("unroll") for (int k = 0; k < 2; ++k) dst[n][k] = *(const PG8_LAS bf16x8*)(lds + PG8_SB(b, h) + boff + n * 2048 + k * 1024); } while (0)
; #define PG8_MMA(ai, bj, At, Bt) do { __builtin_amdgcn_s_setprio(1); _Pragma("unroll") for (int m = 0; m < 4; ++m) _Pragma("unroll") for (int n = 0; n < 2; ++n) _Pragma("unroll") for (int k = 0; k < 2; ++k) \
;         acc[ai][bj][m][n] = __builtin_amdgcn_mfma_f32_16x16x32_bf16(Bt[n][k], At[m][k], acc[ai][bj][m][n], 0, 0, 0); __builtin_amdgcn_s_setprio(0); } while (0)
; #define PG8_WAIT_V(n) asm volatile("s_waitcnt vmcnt(" #n ")" ::: "memory")
; #define PG8_WAIT_L(n) asm volatile("s_waitcnt lgkmcnt(" #n ")" ::: "memory")
; #define PG8_BAR __builtin_amdgcn_s_barrier()
; #define PG8_SCHED __builtin_amdgcn_sched_barrier(0)
; template <class Epi, class Sched, bool ALIGN_EPI = false, bool SP2 = false>
; __device__ __forceinline__ void gemm_phase(PG8_LAS unsigned char* lds, const Gemm g, const Sched& S, const Epi& E) {
;     ...
;             PG8_LDA(At, 0, 1); PG8_STAGE(PG8_SB(0, 0), b2, voffB); PG8_STAGE(PG8_SB(0, 1), b2 + hstep, voffB); PG8_STAGE(PG8_SA(0, 0), a2, voffA);
;             PG8_WAIT_V(8); PG8_WAIT_L(0); PG8_BAR; PG8_MMA(1, 0, At, B0); PG8_MMA(1, 1, At, B1); PG8_BAR; PG8_SCHED;
;             PG8_LDB(B0, 1, 0); PG8_LDB(B1, 1, 1); PG8_SCHED; PG8_LDA(At, 1, 0); PG8_STAGE(PG8_SA(0, 1), a2 + hstep, voffA);
;             PG8_WAIT_V(8); PG8_WAIT_L(0); PG8_BAR; PG8_MMA(0, 0, At, B0); PG8_MMA(0, 1, At, B1); PG8_BAR; PG8_SCHED;
	v_lshl_add_u64 v[198:199], s[60:61], 0, v[128:129]
	s_add_i32 s60, s51, s38
	s_mov_b32 m0, s60
	ds_read_b128 v[174:177], v145 offset:16384
	ds_read_b128 v[178:181], v145 offset:17408
	ds_read_b128 v[182:185], v145 offset:18432
	ds_read_b128 v[186:189], v145 offset:19456
	ds_read_b128 v[190:193], v145 offset:20480
	ds_read_b128 v[194:197], v145 offset:21504
	ds_read_b128 v[202:205], v145 offset:22528
	ds_read_b128 v[206:209], v145 offset:23552
	global_load_lds_dwordx4 v[198:199], off
	v_lshl_add_u64 v[210:211], v[198:199], 0, s[10:11]
	s_add_i32 m0, s60, 0x2000
	s_add_i32 s60, s52, s38
	global_load_lds_dwordx4 v[210:211], off
	v_lshl_add_u64 v[210:211], v[198:199], 0, s[14:15]
	s_mov_b32 m0, s60
	s_nop 0
	global_load_lds_dwordx4 v[210:211], off
	v_lshl_add_u64 v[210:211], v[198:199], 0, s[16:17]
	s_add_i32 m0, s60, 0x2000
	s_nop 0
	global_load_lds_dwordx4 v[210:211], off
	v_lshl_add_u64 v[210:211], s[58:59], 0, v[128:129]
	s_mov_b32 m0, s39
	v_lshl_add_u64 v[212:213], v[210:211], 0, s[10:11]
	global_load_lds_dwordx4 v[210:211], off
	s_mov_b32 m0, s40
	s_nop 0
	global_load_lds_dwordx4 v[212:213], off
	s_waitcnt lgkmcnt(0)
	s_barrier
	s_setprio 1
	s_waitcnt lgkmcnt(0)
	v_mfma_f32_16x16x32_bf16 v[60:63], v[136:139], v[174:177], v[60:63]
	v_mfma_f32_16x16x32_bf16 v[56:59], v[150:153], v[174:177], v[56:59]
	v_mfma_f32_16x16x32_bf16 v[44:47], v[136:139], v[182:185], v[44:47]
	v_mfma_f32_16x16x32_bf16 v[40:43], v[150:153], v[182:185], v[40:43]
	v_mfma_f32_16x16x32_bf16 v[28:31], v[136:139], v[190:193], v[28:31]
	v_mfma_f32_16x16x32_bf16 v[24:27], v[150:153], v[190:193], v[24:27]
	v_mfma_f32_16x16x32_bf16 v[12:15], v[136:139], v[202:205], v[12:15]
	v_mfma_f32_16x16x32_bf16 v[8:11], v[150:153], v[202:205], v[8:11]
	v_mfma_f32_16x16x32_bf16 v[60:63], v[146:149], v[178:181], v[60:63]
	v_mfma_f32_16x16x32_bf16 v[56:59], v[154:157], v[178:181], v[56:59]
	v_mfma_f32_16x16x32_bf16 v[44:47], v[146:149], v[186:189], v[44:47]
	v_mfma_f32_16x16x32_bf16 v[40:43], v[154:157], v[186:189], v[40:43]
	v_mfma_f32_16x16x32_bf16 v[28:31], v[146:149], v[194:197], v[28:31]
	v_mfma_f32_16x16x32_bf16 v[24:27], v[154:157], v[194:197], v[24:27]
	v_mfma_f32_16x16x32_bf16 v[12:15], v[146:149], v[206:209], v[12:15]
	v_mfma_f32_16x16x32_bf16 v[8:11], v[154:157], v[206:209], v[8:11]
	s_setprio 0
	s_setprio 1
	v_mfma_f32_16x16x32_bf16 v[52:55], v[158:161], v[174:177], v[52:55]
	v_mfma_f32_16x16x32_bf16 v[48:51], v[166:169], v[174:177], v[48:51]
	v_mfma_f32_16x16x32_bf16 v[36:39], v[158:161], v[182:185], v[36:39]
	v_mfma_f32_16x16x32_bf16 v[32:35], v[166:169], v[182:185], v[32:35]
	v_mfma_f32_16x16x32_bf16 v[20:23], v[158:161], v[190:193], v[20:23]
	v_mfma_f32_16x16x32_bf16 v[16:19], v[166:169], v[190:193], v[16:19]
	v_mfma_f32_16x16x32_bf16 v[4:7], v[158:161], v[202:205], v[4:7]
	v_mfma_f32_16x16x32_bf16 v[0:3], v[166:169], v[202:205], v[0:3]
	v_mfma_f32_16x16x32_bf16 v[52:55], v[162:165], v[178:181], v[52:55]
	v_mfma_f32_16x16x32_bf16 v[48:51], v[170:173], v[178:181], v[48:51]
	v_mfma_f32_16x16x32_bf16 v[36:39], v[162:165], v[186:189], v[36:39]
	v_mfma_f32_16x16x32_bf16 v[32:35], v[170:173], v[186:189], v[32:35]
	v_mfma_f32_16x16x32_bf16 v[20:23], v[162:165], v[194:197], v[20:23]
	v_mfma_f32_16x16x32_bf16 v[16:19], v[170:173], v[194:197], v[16:19]
	v_mfma_f32_16x16x32_bf16 v[4:7], v[162:165], v[206:209], v[4:7]
	v_mfma_f32_16x16x32_bf16 v[0:3], v[170:173], v[206:209], v[0:3]
	s_setprio 0
	s_waitcnt vmcnt(8)
	s_barrier
	s_add_i32 s58, 0, 0x18000
	v_add_u32_e32 v130, s58, v142
	s_add_i32 s59, 0, 0x1c000
	ds_read_b128 v[136:139], v130
	ds_read_b128 v[146:149], v130 offset:1024
	ds_read_b128 v[150:153], v130 offset:2048
	ds_read_b128 v[154:157], v130 offset:3072
	v_add_u32_e32 v130, s59, v142
	ds_read_b128 v[158:161], v130
	ds_read_b128 v[162:165], v130 offset:1024
	ds_read_b128 v[166:169], v130 offset:2048
	ds_read_b128 v[170:173], v130 offset:3072
	s_mov_b32 m0, s41
	v_lshl_add_u64 v[212:213], v[210:211], 0, s[14:15]
	ds_read_b128 v[174:177], v145 offset:32768
	ds_read_b128 v[178:181], v145 offset:33792
	ds_read_b128 v[182:185], v145 offset:34816
	ds_read_b128 v[186:189], v145 offset:35840
	ds_read_b128 v[190:193], v145 offset:36864
	ds_read_b128 v[194:197], v145 offset:37888
	ds_read_b128 v[202:205], v145 offset:38912
	ds_read_b128 v[206:209], v145 offset:39936
	global_load_lds_dwordx4 v[212:213], off
	v_lshl_add_u64 v[212:213], v[210:211], 0, s[16:17]
	s_mov_b32 m0, s42
	s_nop 0
	global_load_lds_dwordx4 v[212:213], off
	s_waitcnt lgkmcnt(0)
	s_barrier
; #define PG8_STAGE(bufoff, gbase, voff) do { _Pragma("unroll") for (int _i = 0; _i < 2; ++_i) \
;         __builtin_amdgcn_global_load_lds((const unsigned*)((const char*)(gbase) + (voff)[_i]), (PG8_LAS unsigned*)(lds + (bufoff) + ldsw + _i * 8192), 16, 0, 0); } while (0)
; #define PG8_LDA(dst, b, h) do { _Pragma("unroll") for (int m = 0; m < 4; ++m) _Pragma("unroll") for (int k = 0; k < 2; ++k) dst[m][k] = *(const PG8_LAS bf16x8*)(lds + PG8_SA(b, h) + aoff + m * 2048 + k * 1024); } while (0)
; #define PG8_MMA(ai, bj, At, Bt) do { __builtin_amdgcn_s_setprio(1); _Pragma("unroll") for (int m = 0; m < 4; ++m) _Pragma("unroll") for (int n = 0; n < 2; ++n) _Pragma("unroll") for (int k = 0; k < 2; ++k) \
;         acc[ai][bj][m][n] = __builtin_amdgcn_mfma_f32_16x16x32_bf16(Bt[n][k], At[m][k], acc[ai][bj][m][n], 0, 0, 0); __builtin_amdgcn_s_setprio(0); } while (0)
; #define PG8_WAIT_V(n) asm volatile("s_waitcnt vmcnt(" #n ")" ::: "memory")
; #define PG8_WAIT_L(n) asm volatile("s_waitcnt lgkmcnt(" #n ")" ::: "memory")
; #define PG8_BAR __builtin_amdgcn_s_barrier()
; #define PG8_SCHED __builtin_amdgcn_sched_barrier(0)
; template <class Epi, class Sched, bool ALIGN_EPI = false, bool SP2 = false>
; __device__ __forceinline__ void gemm_phase(PG8_LAS unsigned char* lds, const Gemm g, const Sched& S, const Epi& E) {
;     ...
;         for (int t = 0; t < nt; t += 2) {
;     ...
;             PG8_WAIT_V(8); PG8_WAIT_L(0); PG8_BAR; PG8_MMA(0, 0, At, B0); PG8_MMA(0, 1, At, B1); PG8_BAR; PG8_SCHED;
;             PG8_LDA(At, 1, 1); PG8_STAGE(PG8_SB(1, 0), b3, voffB); PG8_STAGE(PG8_SB(1, 1), b3 + hstep, voffB); PG8_STAGE(PG8_SA(1, 0), a3, voffA);
;             PG8_WAIT_V(8); PG8_WAIT_L(0); PG8_BAR; PG8_MMA(1, 0, At, B0); PG8_MMA(1, 1, At, B1); PG8_BAR; PG8_SCHED;
	s_setprio 1
	s_waitcnt lgkmcnt(0)
	v_mfma_f32_16x16x32_bf16 v[124:127], v[136:139], v[174:177], v[124:127]
	v_mfma_f32_16x16x32_bf16 v[120:123], v[150:153], v[174:177], v[120:123]
	v_mfma_f32_16x16x32_bf16 v[108:111], v[136:139], v[182:185], v[108:111]
	v_mfma_f32_16x16x32_bf16 v[104:107], v[150:153], v[182:185], v[104:107]
	v_mfma_f32_16x16x32_bf16 v[92:95], v[136:139], v[190:193], v[92:95]
	v_mfma_f32_16x16x32_bf16 v[88:91], v[150:153], v[190:193], v[88:91]
	v_mfma_f32_16x16x32_bf16 v[76:79], v[136:139], v[202:205], v[76:79]
	v_mfma_f32_16x16x32_bf16 v[72:75], v[150:153], v[202:205], v[72:75]
	v_mfma_f32_16x16x32_bf16 v[124:127], v[146:149], v[178:181], v[124:127]
	v_mfma_f32_16x16x32_bf16 v[120:123], v[154:157], v[178:181], v[120:123]
	v_mfma_f32_16x16x32_bf16 v[108:111], v[146:149], v[186:189], v[108:111]
	v_mfma_f32_16x16x32_bf16 v[104:107], v[154:157], v[186:189], v[104:107]
	v_mfma_f32_16x16x32_bf16 v[92:95], v[146:149], v[194:197], v[92:95]
	v_mfma_f32_16x16x32_bf16 v[88:91], v[154:157], v[194:197], v[88:91]
	v_mfma_f32_16x16x32_bf16 v[76:79], v[146:149], v[206:209], v[76:79]
	v_mfma_f32_16x16x32_bf16 v[72:75], v[154:157], v[206:209], v[72:75]
	s_setprio 0
	s_setprio 1
	v_mfma_f32_16x16x32_bf16 v[116:119], v[158:161], v[174:177], v[116:119]
	v_mfma_f32_16x16x32_bf16 v[112:115], v[166:169], v[174:177], v[112:115]
	v_mfma_f32_16x16x32_bf16 v[100:103], v[158:161], v[182:185], v[100:103]
	v_mfma_f32_16x16x32_bf16 v[96:99], v[166:169], v[182:185], v[96:99]
	v_mfma_f32_16x16x32_bf16 v[84:87], v[158:161], v[190:193], v[84:87]
	v_mfma_f32_16x16x32_bf16 v[80:83], v[166:169], v[190:193], v[80:83]
	v_mfma_f32_16x16x32_bf16 v[68:71], v[158:161], v[202:205], v[68:71]
	v_mfma_f32_16x16x32_bf16 v[64:67], v[166:169], v[202:205], v[64:67]
	v_mfma_f32_16x16x32_bf16 v[116:119], v[162:165], v[178:181], v[116:119]
	v_mfma_f32_16x16x32_bf16 v[112:115], v[170:173], v[178:181], v[112:115]
	v_mfma_f32_16x16x32_bf16 v[100:103], v[162:165], v[186:189], v[100:103]
	v_mfma_f32_16x16x32_bf16 v[96:99], v[170:173], v[186:189], v[96:99]
	v_mfma_f32_16x16x32_bf16 v[84:87], v[162:165], v[194:197], v[84:87]
	v_mfma_f32_16x16x32_bf16 v[80:83], v[170:173], v[194:197], v[80:83]
	v_mfma_f32_16x16x32_bf16 v[68:71], v[162:165], v[206:209], v[68:71]
	v_mfma_f32_16x16x32_bf16 v[64:67], v[170:173], v[206:209], v[64:67]
	s_setprio 0
	s_waitcnt vmcnt(8)
	s_barrier
	s_add_i32 s58, s58, s38
	v_lshl_add_u64 v[212:213], v[198:199], 0, s[20:21]
	s_mov_b32 m0, s58
	ds_read_b128 v[174:177], v145 offset:49152
	ds_read_b128 v[178:181], v145 offset:50176
	ds_read_b128 v[182:185], v145 offset:51200
	ds_read_b128 v[186:189], v145 offset:52224
	ds_read_b128 v[190:193], v145 offset:53248
	ds_read_b128 v[194:197], v145 offset:54272
	ds_read_b128 v[202:205], v145 offset:55296
	ds_read_b128 v[206:209], v145 offset:56320
	global_load_lds_dwordx4 v[212:213], off
	v_lshl_add_u64 v[212:213], v[198:199], 0, s[22:23]
	s_add_i32 m0, s58, 0x2000
	s_add_i32 s58, s59, s38
	global_load_lds_dwordx4 v[212:213], off
	v_lshl_add_u64 v[212:213], v[198:199], 0, s[24:25]
	s_mov_b32 m0, s58
	v_lshl_add_u64 v[198:199], v[198:199], 0, s[26:27]
	global_load_lds_dwordx4 v[212:213], off
	s_add_i32 m0, s58, 0x2000
	s_nop 0
	global_load_lds_dwordx4 v[198:199], off
	v_lshl_add_u64 v[198:199], v[210:211], 0, s[20:21]
	s_mov_b32 m0, s46
	s_nop 0
	global_load_lds_dwordx4 v[198:199], off
	v_lshl_add_u64 v[198:199], v[210:211], 0, s[22:23]
	s_mov_b32 m0, s47
	s_nop 0
	global_load_lds_dwordx4 v[198:199], off
	s_waitcnt lgkmcnt(0)
	s_barrier
	s_setprio 1
	s_waitcnt lgkmcnt(0)
	v_mfma_f32_16x16x32_bf16 v[60:63], v[136:139], v[174:177], v[60:63]
	v_mfma_f32_16x16x32_bf16 v[56:59], v[150:153], v[174:177], v[56:59]
	v_mfma_f32_16x16x32_bf16 v[44:47], v[136:139], v[182:185], v[44:47]
	v_mfma_f32_16x16x32_bf16 v[40:43], v[150:153], v[182:185], v[40:43]
	v_mfma_f32_16x16x32_bf16 v[28:31], v[136:139], v[190:193], v[28:31]
	v_mfma_f32_16x16x32_bf16 v[24:27], v[150:153], v[190:193], v[24:27]
	v_mfma_f32_16x16x32_bf16 v[12:15], v[136:139], v[202:205], v[12:15]
	v_mfma_f32_16x16x32_bf16 v[8:11], v[150:153], v[202:205], v[8:11]
	v_mfma_f32_16x16x32_bf16 v[60:63], v[146:149], v[178:181], v[60:63]
	v_mfma_f32_16x16x32_bf16 v[56:59], v[154:157], v[178:181], v[56:59]
	v_mfma_f32_16x16x32_bf16 v[44:47], v[146:149], v[186:189], v[44:47]
	v_mfma_f32_16x16x32_bf16 v[40:43], v[154:157], v[186:189], v[40:43]
	v_mfma_f32_16x16x32_bf16 v[28:31], v[146:149], v[194:197], v[28:31]
	v_mfma_f32_16x16x32_bf16 v[24:27], v[154:157], v[194:197], v[24:27]
	v_mfma_f32_16x16x32_bf16 v[12:15], v[146:149], v[206:209], v[12:15]
	v_mfma_f32_16x16x32_bf16 v[8:11], v[154:157], v[206:209], v[8:11]
	s_setprio 0
	s_setprio 1
	v_mfma_f32_16x16x32_bf16 v[52:55], v[158:161], v[174:177], v[52:55]
	v_mfma_f32_16x16x32_bf16 v[48:51], v[166:169], v[174:177], v[48:51]
	v_mfma_f32_16x16x32_bf16 v[36:39], v[158:161], v[182:185], v[36:39]
	v_mfma_f32_16x16x32_bf16 v[32:35], v[166:169], v[182:185], v[32:35]
	v_mfma_f32_16x16x32_bf16 v[20:23], v[158:161], v[190:193], v[20:23]
	v_mfma_f32_16x16x32_bf16 v[16:19], v[166:169], v[190:193], v[16:19]
	v_mfma_f32_16x16x32_bf16 v[4:7], v[158:161], v[202:205], v[4:7]
	v_mfma_f32_16x16x32_bf16 v[0:3], v[166:169], v[202:205], v[0:3]
	v_mfma_f32_16x16x32_bf16 v[52:55], v[162:165], v[178:181], v[52:55]
	v_mfma_f32_16x16x32_bf16 v[48:51], v[170:173], v[178:181], v[48:51]
	v_mfma_f32_16x16x32_bf16 v[36:39], v[162:165], v[186:189], v[36:39]
	v_mfma_f32_16x16x32_bf16 v[32:35], v[170:173], v[186:189], v[32:35]
	v_mfma_f32_16x16x32_bf16 v[20:23], v[162:165], v[194:197], v[20:23]
	v_mfma_f32_16x16x32_bf16 v[16:19], v[170:173], v[194:197], v[16:19]
	v_mfma_f32_16x16x32_bf16 v[4:7], v[162:165], v[206:209], v[4:7]
	v_mfma_f32_16x16x32_bf16 v[0:3], v[170:173], v[206:209], v[0:3]
	s_setprio 0
	s_waitcnt vmcnt(8)
	s_barrier
	s_add_i32 s57, s57, 2
	s_add_u32 s12, s12, 0x8000
	s_addc_u32 s13, s13, 0
	s_add_u32 s36, s36, 0x8000
	s_addc_u32 s37, s37, 0
	s_cmp_gt_u32 s57, 41
	s_cbranch_scc0 .LBB0_1424
.Lp5_done:
	s_and_b64 vcc, exec, s[28:29]
	s_cbranch_vccz .LBB0_1427
	s_barrier
